# indexer head loops: packed v_pk_fma_f32 split into two v_fmac_f32 (bit-identical), packed form stalls issue
# baseline (speedup 1.0000x reference)
; #define MFMA32(a, b, c) __builtin_amdgcn_mfma_f32_32x32x16_bf16((a), (b), (c), 0, 0, 0)
; DI void a1_task(unsigned char* shm, const bf16_t* prm, const bf16_t* prt, unsigned* mask, int b, int qt, const int tid) {
;     ...
;             for (int hh = 0; hh < 8; ++hh) {
;                 bf16x8 qa[4];
; #pragma unroll
;                 for (int ks = 0; ks < 4; ++ks) qa[ks] = *(const bf16x8*)(qb0 + hh * 128 + 32 * ks);
;                 const float wv = wqs[hh * 32 + r];
;                 asm volatile("s_waitcnt lgkmcnt(0)" ::: "memory");
;                 f32x16 acc;
; #pragma unroll
;                 for (int i = 0; i < 16; ++i) acc[i] = 0.f;
; #pragma unroll
;                 for (int ks = 0; ks < 4; ++ks) acc = MFMA32(kf[ks], qa[ks], acc);
; #pragma unroll
;                 for (int i = 0; i < 16; ++i) idx[i] = fmaf(wv, fmaxf(acc[i], 0.f), idx[i]);
;             }
; #pragma unroll
;             for (int i = 0; i < 16; ++i) {
;                 const int s = s0 + 16 * (i >> 3) + 8 * h + (i & 7);
;                 const unsigned u = __float_as_uint(idx[i] + 0.0f);
;                 const unsigned k = (u & 0x80000000u) ? ~u : (u | 0x80000000u);
;                 key[jt][i] = (s <= t0 + r) ? k : 0u;
;             }
;             if (hn) {
; #pragma unroll
;                 for (int ks = 0; ks < 4; ++ks) kf[ks] = kn[ks];
.LBB0_389:
	v_add_u32_e32 v79, s1, v118
	ds_read_b128 v[2:5], v79
	ds_read_b128 v[66:69], v79 offset:32
	ds_read_b128 v[70:73], v79 offset:64
	ds_read_b128 v[74:77], v79 offset:96
	v_add_u32_e32 v80, s1, v135
	s_waitcnt lgkmcnt(3)
	v_mfma_f32_32x32x16_bf16 v[2:17], v[50:53], v[2:5], 0
	ds_read_b32 v78, v80
	s_waitcnt lgkmcnt(0)
	s_addk_i32 s1, 0x100
	s_cmpk_eq_i32 s1, 0x400
	s_waitcnt lgkmcnt(3)
	v_mfma_f32_32x32x16_bf16 v[2:17], v[54:57], v[66:69], v[2:17]
	s_waitcnt lgkmcnt(2)
	v_mfma_f32_32x32x16_bf16 v[2:17], v[58:61], v[70:73], v[2:17]
	s_waitcnt lgkmcnt(1)
	v_mfma_f32_32x32x16_bf16 v[2:17], v[62:65], v[74:77], v[2:17]
	s_nop 11
	v_max_f32_e32 v2, 0, v2
	v_max_f32_e32 v3, 0, v3
	s_waitcnt lgkmcnt(0)
	v_fmac_f32_e32 v48, v78, v2
	v_fmac_f32_e32 v49, v78, v3
	v_max_f32_e32 v2, 0, v4
	v_max_f32_e32 v3, 0, v5
	v_fmac_f32_e32 v46, v78, v2
	v_fmac_f32_e32 v47, v78, v3
	v_max_f32_e32 v2, 0, v6
	v_max_f32_e32 v3, 0, v7
	v_fmac_f32_e32 v44, v78, v2
	v_fmac_f32_e32 v45, v78, v3
	v_max_f32_e32 v2, 0, v8
	v_max_f32_e32 v3, 0, v9
	v_fmac_f32_e32 v42, v78, v2
	v_fmac_f32_e32 v43, v78, v3
	v_max_f32_e32 v2, 0, v10
	v_max_f32_e32 v3, 0, v11
	v_fmac_f32_e32 v40, v78, v2
	v_fmac_f32_e32 v41, v78, v3
	v_max_f32_e32 v2, 0, v12
	v_max_f32_e32 v3, 0, v13
	v_fmac_f32_e32 v38, v78, v2
	v_fmac_f32_e32 v39, v78, v3
	v_max_f32_e32 v2, 0, v14
	v_max_f32_e32 v3, 0, v15
	v_fmac_f32_e32 v36, v78, v2
	v_fmac_f32_e32 v37, v78, v3
	v_max_f32_e32 v2, 0, v16
	v_max_f32_e32 v3, 0, v17
	v_fmac_f32_e32 v34, v78, v2
	v_fmac_f32_e32 v35, v78, v3
	ds_read_b128 v[2:5], v79 offset:128
	ds_read_b128 v[66:69], v79 offset:160
	ds_read_b128 v[70:73], v79 offset:192
	ds_read_b128 v[74:77], v79 offset:224
	ds_read_b32 v78, v80 offset:128
	s_waitcnt lgkmcnt(4)
	v_mfma_f32_32x32x16_bf16 v[2:17], v[50:53], v[2:5], 0
	s_waitcnt lgkmcnt(0)
	s_waitcnt lgkmcnt(3)
	v_mfma_f32_32x32x16_bf16 v[2:17], v[54:57], v[66:69], v[2:17]
	s_waitcnt lgkmcnt(2)
	v_mfma_f32_32x32x16_bf16 v[2:17], v[58:61], v[70:73], v[2:17]
	s_waitcnt lgkmcnt(1)
	v_mfma_f32_32x32x16_bf16 v[2:17], v[62:65], v[74:77], v[2:17]
	s_nop 11
	v_max_f32_e32 v2, 0, v2
	v_max_f32_e32 v3, 0, v3
	s_waitcnt lgkmcnt(0)
	v_fmac_f32_e32 v48, v78, v2
	v_fmac_f32_e32 v49, v78, v3
	v_max_f32_e32 v2, 0, v4
	v_max_f32_e32 v3, 0, v5
	v_fmac_f32_e32 v46, v78, v2
	v_fmac_f32_e32 v47, v78, v3
	v_max_f32_e32 v2, 0, v6
	v_max_f32_e32 v3, 0, v7
	v_fmac_f32_e32 v44, v78, v2
	v_fmac_f32_e32 v45, v78, v3
	v_max_f32_e32 v2, 0, v8
	v_max_f32_e32 v3, 0, v9
	v_fmac_f32_e32 v42, v78, v2
	v_fmac_f32_e32 v43, v78, v3
	v_max_f32_e32 v2, 0, v10
	v_max_f32_e32 v3, 0, v11
	v_fmac_f32_e32 v40, v78, v2
	v_fmac_f32_e32 v41, v78, v3
	v_max_f32_e32 v2, 0, v12
	v_max_f32_e32 v3, 0, v13
	v_fmac_f32_e32 v38, v78, v2
	v_fmac_f32_e32 v39, v78, v3
	v_max_f32_e32 v2, 0, v14
	v_max_f32_e32 v3, 0, v15
	v_fmac_f32_e32 v36, v78, v2
	v_fmac_f32_e32 v37, v78, v3
	v_max_f32_e32 v2, 0, v16
	v_max_f32_e32 v3, 0, v17
	v_fmac_f32_e32 v34, v78, v2
	v_fmac_f32_e32 v35, v78, v3
	s_cbranch_scc0 .LBB0_389
	v_or_b32_e32 v66, s0, v98
	v_or_b32_e32 v2, 3, v66
	v_or_b32_e32 v3, 2, v66
	v_cmp_le_i32_e64 s[92:93], v3, v0
	v_cmp_le_i32_e64 s[94:95], v2, v0
	v_or_b32_e32 v2, 5, v66
	v_or_b32_e32 v3, 4, v66
	v_cmp_le_i32_e64 s[84:85], v3, v0
	v_cmp_le_i32_e64 s[86:87], v2, v0
	v_or_b32_e32 v2, 7, v66
	v_or_b32_e32 v3, 6, v66
	v_cmp_le_i32_e64 s[76:77], v3, v0
	v_cmp_le_i32_e64 s[78:79], v2, v0
	v_or_b32_e32 v2, 17, v66
	v_or_b32_e32 v3, 16, v66
	v_cmp_le_i32_e64 s[68:69], v3, v0
	v_cmp_le_i32_e64 s[70:71], v2, v0
	v_or_b32_e32 v2, 19, v66
	v_or_b32_e32 v3, 18, v66
	v_cmp_le_i32_e64 s[60:61], v3, v0
	v_cmp_le_i32_e64 s[62:63], v2, v0
	v_or_b32_e32 v2, 21, v66
	v_or_b32_e32 v3, 20, v66
	v_cmp_le_i32_e64 s[52:53], v3, v0
	v_cmp_le_i32_e64 s[54:55], v2, v0
	v_pk_add_f32 v[2:3], v[34:35], 0 op_sel_hi:[1,0]
	v_or_b32_e32 v34, 23, v66
	v_or_b32_e32 v35, 22, v66
	v_pk_add_f32 v[16:17], v[48:49], 0 op_sel_hi:[1,0]
	v_pk_add_f32 v[14:15], v[46:47], 0 op_sel_hi:[1,0]
	v_pk_add_f32 v[12:13], v[44:45], 0 op_sel_hi:[1,0]
	v_pk_add_f32 v[10:11], v[42:43], 0 op_sel_hi:[1,0]
	v_pk_add_f32 v[8:9], v[40:41], 0 op_sel_hi:[1,0]
	v_pk_add_f32 v[6:7], v[38:39], 0 op_sel_hi:[1,0]
	v_pk_add_f32 v[4:5], v[36:37], 0 op_sel_hi:[1,0]
	v_cmp_le_i32_e64 s[42:43], v35, v0
	v_cmp_le_i32_e64 s[44:45], v34, v0
	v_mov_b64_e32 v[34:35], v[50:51]
	v_mov_b64_e32 v[38:39], v[54:55]
	v_mov_b64_e32 v[42:43], v[58:59]
	v_mov_b64_e32 v[46:47], v[62:63]
	v_cmp_gt_i32_e64 s[46:47], 0, v17
	v_cmp_gt_i32_e64 s[6:7], 0, v16
	v_cmp_le_i32_e64 s[8:9], v66, v0
	v_cmp_lt_i32_e64 s[4:5], v66, v0
	v_cmp_gt_i32_e64 s[90:91], 0, v14
	v_cmp_gt_i32_e64 s[96:97], 0, v15
	v_cmp_gt_i32_e64 s[82:83], 0, v12
	v_cmp_gt_i32_e64 s[88:89], 0, v13
	v_cmp_gt_i32_e64 s[74:75], 0, v10
	v_cmp_gt_i32_e64 s[80:81], 0, v11
	v_cmp_gt_i32_e64 s[66:67], 0, v8
	v_cmp_gt_i32_e64 s[72:73], 0, v9
	v_cmp_gt_i32_e64 s[58:59], 0, v6
	v_cmp_gt_i32_e64 s[64:65], 0, v7
	v_cmp_gt_i32_e64 s[50:51], 0, v4
	v_cmp_gt_i32_e64 s[56:57], 0, v5
	v_cmp_gt_i32_e64 s[0:1], 0, v2
	v_cmp_gt_i32_e64 s[48:49], 0, v3
	s_and_b64 vcc, exec, vcc
	v_mov_b64_e32 v[36:37], v[52:53]
	v_mov_b64_e32 v[40:41], v[56:57]
	v_mov_b64_e32 v[44:45], v[60:61]
	v_mov_b64_e32 v[48:49], v[64:65]
	s_cbranch_vccz .LBB0_392
	s_waitcnt vmcnt(0)
	v_mov_b64_e32 v[36:37], v[20:21]
	v_mov_b64_e32 v[40:41], v[24:25]
	v_mov_b64_e32 v[44:45], v[28:29]
	v_mov_b64_e32 v[48:49], v[32:33]
	v_mov_b64_e32 v[34:35], v[18:19]
	v_mov_b64_e32 v[38:39], v[22:23]
	v_mov_b64_e32 v[42:43], v[26:27]
	v_mov_b64_e32 v[46:47], v[30:31]

; #define MFMA32(a, b, c) __builtin_amdgcn_mfma_f32_32x32x16_bf16((a), (b), (c), 0, 0, 0)
; DI void a1_task(unsigned char* shm, const bf16_t* prm, const bf16_t* prt, unsigned* mask, int b, int qt, const int tid) {
;     ...
;             for (int hh = 0; hh < 8; ++hh) {
;                 bf16x8 qa[4];
; #pragma unroll
;                 for (int ks = 0; ks < 4; ++ks) qa[ks] = *(const bf16x8*)(qb0 + hh * 128 + 32 * ks);
;                 const float wv = wqs[hh * 32 + r];
;                 asm volatile("s_waitcnt lgkmcnt(0)" ::: "memory");
;                 f32x16 acc;
; #pragma unroll
;                 for (int i = 0; i < 16; ++i) acc[i] = 0.f;
; #pragma unroll
;                 for (int ks = 0; ks < 4; ++ks) acc = MFMA32(kf[ks], qa[ks], acc);
; #pragma unroll
;                 for (int i = 0; i < 16; ++i) idx[i] = fmaf(wv, fmaxf(acc[i], 0.f), idx[i]);
;             }
; #pragma unroll
;             for (int i = 0; i < 16; ++i) {
;                 const int s = s0 + 16 * (i >> 3) + 8 * h + (i & 7);
;                 const unsigned u = __float_as_uint(idx[i] + 0.0f);
;                 const unsigned k = (u & 0x80000000u) ? ~u : (u | 0x80000000u);
;                 key[jt][i] = (s <= t0 + r) ? k : 0u;
;             }
;             if (hn) {
; #pragma unroll
;                 for (int ks = 0; ks < 4; ++ks) kf[ks] = kn[ks];
.LBB0_399:
	v_add_u32_e32 v79, s1, v118
	ds_read_b128 v[2:5], v79
	ds_read_b128 v[66:69], v79 offset:32
	ds_read_b128 v[70:73], v79 offset:64
	ds_read_b128 v[74:77], v79 offset:96
	v_add_u32_e32 v80, s1, v135
	s_waitcnt lgkmcnt(3)
	v_mfma_f32_32x32x16_bf16 v[2:17], v[34:37], v[2:5], 0
	ds_read_b32 v78, v80
	s_waitcnt lgkmcnt(0)
	s_addk_i32 s1, 0x100
	s_cmpk_lg_i32 s1, 0x400
	s_waitcnt lgkmcnt(3)
	v_mfma_f32_32x32x16_bf16 v[2:17], v[38:41], v[66:69], v[2:17]
	s_waitcnt lgkmcnt(2)
	v_mfma_f32_32x32x16_bf16 v[2:17], v[42:45], v[70:73], v[2:17]
	s_waitcnt lgkmcnt(1)
	v_mfma_f32_32x32x16_bf16 v[2:17], v[46:49], v[74:77], v[2:17]
	s_nop 11
	v_max_f32_e32 v2, 0, v2
	v_max_f32_e32 v3, 0, v3
	s_waitcnt lgkmcnt(0)
	v_fmac_f32_e32 v64, v78, v2
	v_fmac_f32_e32 v65, v78, v3
	v_max_f32_e32 v2, 0, v4
	v_max_f32_e32 v3, 0, v5
	v_fmac_f32_e32 v62, v78, v2
	v_fmac_f32_e32 v63, v78, v3
	v_max_f32_e32 v2, 0, v6
	v_max_f32_e32 v3, 0, v7
	v_fmac_f32_e32 v60, v78, v2
	v_fmac_f32_e32 v61, v78, v3
	v_max_f32_e32 v2, 0, v8
	v_max_f32_e32 v3, 0, v9
	v_fmac_f32_e32 v58, v78, v2
	v_fmac_f32_e32 v59, v78, v3
	v_max_f32_e32 v2, 0, v10
	v_max_f32_e32 v3, 0, v11
	v_fmac_f32_e32 v56, v78, v2
	v_fmac_f32_e32 v57, v78, v3
	v_max_f32_e32 v2, 0, v12
	v_max_f32_e32 v3, 0, v13
	v_fmac_f32_e32 v54, v78, v2
	v_fmac_f32_e32 v55, v78, v3
	v_max_f32_e32 v2, 0, v14
	v_max_f32_e32 v3, 0, v15
	v_fmac_f32_e32 v52, v78, v2
	v_fmac_f32_e32 v53, v78, v3
	v_max_f32_e32 v2, 0, v16
	v_max_f32_e32 v3, 0, v17
	v_fmac_f32_e32 v50, v78, v2
	v_fmac_f32_e32 v51, v78, v3
	ds_read_b128 v[2:5], v79 offset:128
	ds_read_b128 v[66:69], v79 offset:160
	ds_read_b128 v[70:73], v79 offset:192
	ds_read_b128 v[74:77], v79 offset:224
	ds_read_b32 v78, v80 offset:128
	s_waitcnt lgkmcnt(4)
	v_mfma_f32_32x32x16_bf16 v[2:17], v[34:37], v[2:5], 0
	s_waitcnt lgkmcnt(0)
	s_waitcnt lgkmcnt(3)
	v_mfma_f32_32x32x16_bf16 v[2:17], v[38:41], v[66:69], v[2:17]
	s_waitcnt lgkmcnt(2)
	v_mfma_f32_32x32x16_bf16 v[2:17], v[42:45], v[70:73], v[2:17]
	s_waitcnt lgkmcnt(1)
	v_mfma_f32_32x32x16_bf16 v[2:17], v[46:49], v[74:77], v[2:17]
	s_nop 11
	v_max_f32_e32 v2, 0, v2
	v_max_f32_e32 v3, 0, v3
	s_waitcnt lgkmcnt(0)
	v_fmac_f32_e32 v64, v78, v2
	v_fmac_f32_e32 v65, v78, v3
	v_max_f32_e32 v2, 0, v4
	v_max_f32_e32 v3, 0, v5
	v_fmac_f32_e32 v62, v78, v2
	v_fmac_f32_e32 v63, v78, v3
	v_max_f32_e32 v2, 0, v6
	v_max_f32_e32 v3, 0, v7
	v_fmac_f32_e32 v60, v78, v2
	v_fmac_f32_e32 v61, v78, v3
	v_max_f32_e32 v2, 0, v8
	v_max_f32_e32 v3, 0, v9
	v_fmac_f32_e32 v58, v78, v2
	v_fmac_f32_e32 v59, v78, v3
	v_max_f32_e32 v2, 0, v10
	v_max_f32_e32 v3, 0, v11
	v_fmac_f32_e32 v56, v78, v2
	v_fmac_f32_e32 v57, v78, v3
	v_max_f32_e32 v2, 0, v12
	v_max_f32_e32 v3, 0, v13
	v_fmac_f32_e32 v54, v78, v2
	v_fmac_f32_e32 v55, v78, v3
	v_max_f32_e32 v2, 0, v14
	v_max_f32_e32 v3, 0, v15
	v_fmac_f32_e32 v52, v78, v2
	v_fmac_f32_e32 v53, v78, v3
	v_max_f32_e32 v2, 0, v16
	v_max_f32_e32 v3, 0, v17
	v_fmac_f32_e32 v50, v78, v2
	v_fmac_f32_e32 v51, v78, v3
	s_cbranch_scc1 .LBB0_399
	v_or_b32_e32 v66, s0, v98
	v_or_b32_e32 v2, 3, v66
	v_or_b32_e32 v3, 2, v66
	v_cmp_le_i32_e64 s[92:93], v3, v0
	v_cmp_le_i32_e64 s[94:95], v2, v0
	v_or_b32_e32 v2, 5, v66
	v_or_b32_e32 v3, 4, v66
	v_cmp_le_i32_e64 s[84:85], v3, v0
	v_cmp_le_i32_e64 s[86:87], v2, v0
	v_or_b32_e32 v2, 7, v66
	v_or_b32_e32 v3, 6, v66
	v_cmp_le_i32_e64 s[76:77], v3, v0
	v_cmp_le_i32_e64 s[78:79], v2, v0
	v_or_b32_e32 v2, 17, v66
	v_or_b32_e32 v3, 16, v66
	v_cmp_le_i32_e64 s[68:69], v3, v0
	v_cmp_le_i32_e64 s[70:71], v2, v0
	v_or_b32_e32 v2, 19, v66
	v_or_b32_e32 v3, 18, v66
	v_cmp_le_i32_e64 s[60:61], v3, v0
	v_cmp_le_i32_e64 s[62:63], v2, v0
	v_or_b32_e32 v2, 21, v66
	v_or_b32_e32 v3, 20, v66
	v_pk_add_f32 v[16:17], v[64:65], 0 op_sel_hi:[1,0]
	v_pk_add_f32 v[14:15], v[62:63], 0 op_sel_hi:[1,0]
	v_pk_add_f32 v[12:13], v[60:61], 0 op_sel_hi:[1,0]
	v_pk_add_f32 v[10:11], v[58:59], 0 op_sel_hi:[1,0]
	v_pk_add_f32 v[8:9], v[56:57], 0 op_sel_hi:[1,0]
	v_pk_add_f32 v[6:7], v[54:55], 0 op_sel_hi:[1,0]
	v_pk_add_f32 v[4:5], v[52:53], 0 op_sel_hi:[1,0]
	v_cmp_le_i32_e64 s[50:51], v3, v0
	v_cmp_le_i32_e64 s[52:53], v2, v0
	v_pk_add_f32 v[2:3], v[50:51], 0 op_sel_hi:[1,0]
	v_or_b32_e32 v50, 23, v66
	v_or_b32_e32 v51, 22, v66
	v_cmp_gt_i32_e64 s[46:47], 0, v17
	v_cmp_gt_i32_e64 s[6:7], 0, v16
	v_cmp_le_i32_e64 s[8:9], v66, v0
	v_cmp_lt_i32_e64 s[4:5], v66, v0
	v_cmp_gt_i32_e64 s[90:91], 0, v14
	v_cmp_gt_i32_e64 s[96:97], 0, v15
	v_cmp_gt_i32_e64 s[82:83], 0, v12
	v_cmp_gt_i32_e64 s[88:89], 0, v13
	v_cmp_gt_i32_e64 s[74:75], 0, v10
	v_cmp_gt_i32_e64 s[80:81], 0, v11
	v_cmp_gt_i32_e64 s[66:67], 0, v8
	v_cmp_gt_i32_e64 s[72:73], 0, v9
	v_cmp_gt_i32_e64 s[58:59], 0, v6
	v_cmp_gt_i32_e64 s[64:65], 0, v7
	v_cmp_gt_i32_e64 s[48:49], 0, v4
	v_cmp_gt_i32_e64 s[56:57], 0, v5
	v_cmp_gt_i32_e64 s[0:1], 0, v2
	v_cmp_gt_i32_e64 s[44:45], 0, v3
	v_cmp_le_i32_e64 s[42:43], v51, v0
	s_andn2_b64 vcc, exec, s[40:41]
	v_cmp_le_i32_e64 s[54:55], v50, v0
	s_cbranch_vccnz .LBB0_402
	s_waitcnt vmcnt(0)
	v_mov_b64_e32 v[36:37], v[20:21]
	v_mov_b64_e32 v[40:41], v[24:25]
	v_mov_b64_e32 v[44:45], v[28:29]
	v_mov_b64_e32 v[48:49], v[32:33]
	v_mov_b64_e32 v[34:35], v[18:19]
	v_mov_b64_e32 v[38:39], v[22:23]
	v_mov_b64_e32 v[42:43], v[26:27]
	v_mov_b64_e32 v[46:47], v[30:31]

; #define MFMA32(a, b, c) __builtin_amdgcn_mfma_f32_32x32x16_bf16((a), (b), (c), 0, 0, 0)
; DI void a1_task(unsigned char* shm, const bf16_t* prm, const bf16_t* prt, unsigned* mask, int b, int qt, const int tid) {
;     ...
;             for (int hh = 0; hh < 8; ++hh) {
;                 bf16x8 qa[4];
; #pragma unroll
;                 for (int ks = 0; ks < 4; ++ks) qa[ks] = *(const bf16x8*)(qb0 + hh * 128 + 32 * ks);
;                 const float wv = wqs[hh * 32 + r];
;                 asm volatile("s_waitcnt lgkmcnt(0)" ::: "memory");
;                 f32x16 acc;
; #pragma unroll
;                 for (int i = 0; i < 16; ++i) acc[i] = 0.f;
; #pragma unroll
;                 for (int ks = 0; ks < 4; ++ks) acc = MFMA32(kf[ks], qa[ks], acc);
; #pragma unroll
;                 for (int i = 0; i < 16; ++i) idx[i] = fmaf(wv, fmaxf(acc[i], 0.f), idx[i]);
;             }
; #pragma unroll
;             for (int i = 0; i < 16; ++i) {
;                 const int s = s0 + 16 * (i >> 3) + 8 * h + (i & 7);
;                 const unsigned u = __float_as_uint(idx[i] + 0.0f);
;                 const unsigned k = (u & 0x80000000u) ? ~u : (u | 0x80000000u);
;                 key[jt][i] = (s <= t0 + r) ? k : 0u;
;             }
;             if (hn) {
; #pragma unroll
;                 for (int ks = 0; ks < 4; ++ks) kf[ks] = kn[ks];
.LBB0_408:
	v_add_u32_e32 v95, s1, v118
	ds_read_b128 v[2:5], v95
	ds_read_b128 v[82:85], v95 offset:32
	ds_read_b128 v[86:89], v95 offset:64
	ds_read_b128 v[90:93], v95 offset:96
	v_add_u32_e32 v96, s1, v135
	s_waitcnt lgkmcnt(3)
	v_mfma_f32_32x32x16_bf16 v[2:17], v[34:37], v[2:5], 0
	ds_read_b32 v94, v96
	s_waitcnt lgkmcnt(0)
	s_addk_i32 s1, 0x100
	s_cmpk_lg_i32 s1, 0x400
	s_waitcnt lgkmcnt(3)
	v_mfma_f32_32x32x16_bf16 v[2:17], v[38:41], v[82:85], v[2:17]
	s_waitcnt lgkmcnt(2)
	v_mfma_f32_32x32x16_bf16 v[2:17], v[42:45], v[86:89], v[2:17]
	s_waitcnt lgkmcnt(1)
	v_mfma_f32_32x32x16_bf16 v[2:17], v[46:49], v[90:93], v[2:17]
	s_nop 11
	v_max_f32_e32 v2, 0, v2
	v_max_f32_e32 v3, 0, v3
	s_waitcnt lgkmcnt(0)
	v_fmac_f32_e32 v80, v94, v2
	v_fmac_f32_e32 v81, v94, v3
	v_max_f32_e32 v2, 0, v4
	v_max_f32_e32 v3, 0, v5
	v_fmac_f32_e32 v78, v94, v2
	v_fmac_f32_e32 v79, v94, v3
	v_max_f32_e32 v2, 0, v6
	v_max_f32_e32 v3, 0, v7
	v_fmac_f32_e32 v76, v94, v2
	v_fmac_f32_e32 v77, v94, v3
	v_max_f32_e32 v2, 0, v8
	v_max_f32_e32 v3, 0, v9
	v_fmac_f32_e32 v74, v94, v2
	v_fmac_f32_e32 v75, v94, v3
	v_max_f32_e32 v2, 0, v10
	v_max_f32_e32 v3, 0, v11
	v_fmac_f32_e32 v72, v94, v2
	v_fmac_f32_e32 v73, v94, v3
	v_max_f32_e32 v2, 0, v12
	v_max_f32_e32 v3, 0, v13
	v_fmac_f32_e32 v70, v94, v2
	v_fmac_f32_e32 v71, v94, v3
	v_max_f32_e32 v2, 0, v14
	v_max_f32_e32 v3, 0, v15
	v_fmac_f32_e32 v68, v94, v2
	v_fmac_f32_e32 v69, v94, v3
	v_max_f32_e32 v2, 0, v16
	v_max_f32_e32 v3, 0, v17
	v_fmac_f32_e32 v66, v94, v2
	v_fmac_f32_e32 v67, v94, v3
	ds_read_b128 v[2:5], v95 offset:128
	ds_read_b128 v[82:85], v95 offset:160
	ds_read_b128 v[86:89], v95 offset:192
	ds_read_b128 v[90:93], v95 offset:224
	ds_read_b32 v94, v96 offset:128
	s_waitcnt lgkmcnt(4)
	v_mfma_f32_32x32x16_bf16 v[2:17], v[34:37], v[2:5], 0
	s_waitcnt lgkmcnt(0)
	s_waitcnt lgkmcnt(3)
	v_mfma_f32_32x32x16_bf16 v[2:17], v[38:41], v[82:85], v[2:17]
	s_waitcnt lgkmcnt(2)
	v_mfma_f32_32x32x16_bf16 v[2:17], v[42:45], v[86:89], v[2:17]
	s_waitcnt lgkmcnt(1)
	v_mfma_f32_32x32x16_bf16 v[2:17], v[46:49], v[90:93], v[2:17]
	s_nop 11
	v_max_f32_e32 v2, 0, v2
	v_max_f32_e32 v3, 0, v3
	s_waitcnt lgkmcnt(0)
	v_fmac_f32_e32 v80, v94, v2
	v_fmac_f32_e32 v81, v94, v3
	v_max_f32_e32 v2, 0, v4
	v_max_f32_e32 v3, 0, v5
	v_fmac_f32_e32 v78, v94, v2
	v_fmac_f32_e32 v79, v94, v3
	v_max_f32_e32 v2, 0, v6
	v_max_f32_e32 v3, 0, v7
	v_fmac_f32_e32 v76, v94, v2
	v_fmac_f32_e32 v77, v94, v3
	v_max_f32_e32 v2, 0, v8
	v_max_f32_e32 v3, 0, v9
	v_fmac_f32_e32 v74, v94, v2
	v_fmac_f32_e32 v75, v94, v3
	v_max_f32_e32 v2, 0, v10
	v_max_f32_e32 v3, 0, v11
	v_fmac_f32_e32 v72, v94, v2
	v_fmac_f32_e32 v73, v94, v3
	v_max_f32_e32 v2, 0, v12
	v_max_f32_e32 v3, 0, v13
	v_fmac_f32_e32 v70, v94, v2
	v_fmac_f32_e32 v71, v94, v3
	v_max_f32_e32 v2, 0, v14
	v_max_f32_e32 v3, 0, v15
	v_fmac_f32_e32 v68, v94, v2
	v_fmac_f32_e32 v69, v94, v3
	v_max_f32_e32 v2, 0, v16
	v_max_f32_e32 v3, 0, v17
	v_fmac_f32_e32 v66, v94, v2
	v_fmac_f32_e32 v67, v94, v3
	s_cbranch_scc1 .LBB0_408
	v_or_b32_e32 v82, s0, v98
	v_or_b32_e32 v2, 3, v82
	v_or_b32_e32 v3, 2, v82
	v_cmp_le_i32_e64 s[92:93], v3, v0
	v_cmp_le_i32_e64 s[94:95], v2, v0
	v_or_b32_e32 v2, 5, v82
	v_or_b32_e32 v3, 4, v82
	v_cmp_le_i32_e64 s[84:85], v3, v0
	v_cmp_le_i32_e64 s[86:87], v2, v0
	v_or_b32_e32 v2, 7, v82
	v_or_b32_e32 v3, 6, v82
	v_cmp_le_i32_e64 s[76:77], v3, v0
	v_cmp_le_i32_e64 s[78:79], v2, v0
	v_or_b32_e32 v2, 17, v82
	v_or_b32_e32 v3, 16, v82
	v_cmp_le_i32_e64 s[68:69], v3, v0
	v_cmp_le_i32_e64 s[70:71], v2, v0
	v_or_b32_e32 v2, 19, v82
	v_or_b32_e32 v3, 18, v82
	v_cmp_le_i32_e64 s[60:61], v3, v0
	v_cmp_le_i32_e64 s[62:63], v2, v0
	v_or_b32_e32 v2, 21, v82
	v_or_b32_e32 v3, 20, v82
	v_cmp_le_i32_e64 s[52:53], v3, v0
	v_cmp_le_i32_e64 s[54:55], v2, v0
	v_pk_add_f32 v[2:3], v[66:67], 0 op_sel_hi:[1,0]
	v_or_b32_e32 v66, 23, v82
	v_or_b32_e32 v67, 22, v82
	v_pk_add_f32 v[16:17], v[80:81], 0 op_sel_hi:[1,0]
	v_cmp_le_i32_e64 s[8:9], v82, v0
	v_cmp_lt_i32_e64 s[4:5], v82, v0
	v_pk_add_f32 v[14:15], v[78:79], 0 op_sel_hi:[1,0]
	v_pk_add_f32 v[12:13], v[76:77], 0 op_sel_hi:[1,0]
	v_pk_add_f32 v[10:11], v[74:75], 0 op_sel_hi:[1,0]
	v_pk_add_f32 v[8:9], v[72:73], 0 op_sel_hi:[1,0]
	v_pk_add_f32 v[6:7], v[70:71], 0 op_sel_hi:[1,0]
	v_pk_add_f32 v[4:5], v[68:69], 0 op_sel_hi:[1,0]
	v_cmp_le_i32_e64 s[42:43], v67, v0
	v_cmp_le_i32_e64 s[44:45], v66, v0
	v_mov_b64_e32 v[68:69], v[36:37]
	v_mov_b64_e32 v[76:77], v[40:41]
	v_mov_b64_e32 v[84:85], v[44:45]
	v_mov_b64_e32 v[92:93], v[48:49]
	v_cmp_gt_i32_e64 s[96:97], 0, v17
	v_cmp_gt_i32_e64 s[6:7], 0, v16
	v_cmp_gt_i32_e64 s[90:91], 0, v14
	v_cmp_gt_i32_e64 s[46:47], 0, v15
	v_cmp_gt_i32_e64 s[82:83], 0, v12
	v_cmp_gt_i32_e64 s[88:89], 0, v13
	v_cmp_gt_i32_e64 s[74:75], 0, v10
	v_cmp_gt_i32_e64 s[80:81], 0, v11
	v_cmp_gt_i32_e64 s[66:67], 0, v8
	v_cmp_gt_i32_e64 s[72:73], 0, v9
	v_cmp_gt_i32_e64 s[58:59], 0, v6
	v_cmp_gt_i32_e64 s[64:65], 0, v7
	v_cmp_gt_i32_e64 s[50:51], 0, v4
	v_cmp_gt_i32_e64 s[56:57], 0, v5
	v_cmp_gt_i32_e64 s[0:1], 0, v2
	v_cmp_gt_i32_e64 s[48:49], 0, v3
	s_andn2_b64 vcc, exec, s[40:41]
	v_mov_b64_e32 v[66:67], v[34:35]
	v_mov_b64_e32 v[74:75], v[38:39]
	v_mov_b64_e32 v[82:83], v[42:43]
	v_mov_b64_e32 v[90:91], v[46:47]
	s_cbranch_vccnz .LBB0_411
	s_waitcnt vmcnt(3)
	v_mov_b64_e32 v[68:69], v[52:53]
	s_waitcnt vmcnt(2)
	v_mov_b64_e32 v[76:77], v[56:57]
	s_waitcnt vmcnt(1)
	v_mov_b64_e32 v[84:85], v[60:61]
	s_waitcnt vmcnt(0)
	v_mov_b64_e32 v[92:93], v[64:65]
	v_mov_b64_e32 v[66:67], v[50:51]
	v_mov_b64_e32 v[74:75], v[54:55]
	v_mov_b64_e32 v[82:83], v[58:59]
	v_mov_b64_e32 v[90:91], v[62:63]

; #define MFMA32(a, b, c) __builtin_amdgcn_mfma_f32_32x32x16_bf16((a), (b), (c), 0, 0, 0)
; DI void a1_task(unsigned char* shm, const bf16_t* prm, const bf16_t* prt, unsigned* mask, int b, int qt, const int tid) {
;     ...
;             for (int hh = 0; hh < 8; ++hh) {
;                 bf16x8 qa[4];
; #pragma unroll
;                 for (int ks = 0; ks < 4; ++ks) qa[ks] = *(const bf16x8*)(qb0 + hh * 128 + 32 * ks);
;                 const float wv = wqs[hh * 32 + r];
;                 asm volatile("s_waitcnt lgkmcnt(0)" ::: "memory");
;                 f32x16 acc;
; #pragma unroll
;                 for (int i = 0; i < 16; ++i) acc[i] = 0.f;
; #pragma unroll
;                 for (int ks = 0; ks < 4; ++ks) acc = MFMA32(kf[ks], qa[ks], acc);
; #pragma unroll
;                 for (int i = 0; i < 16; ++i) idx[i] = fmaf(wv, fmaxf(acc[i], 0.f), idx[i]);
;             }
; #pragma unroll
;             for (int i = 0; i < 16; ++i) {
;                 const int s = s0 + 16 * (i >> 3) + 8 * h + (i & 7);
;                 const unsigned u = __float_as_uint(idx[i] + 0.0f);
;                 const unsigned k = (u & 0x80000000u) ? ~u : (u | 0x80000000u);
;                 key[jt][i] = (s <= t0 + r) ? k : 0u;
;             }
;             if (hn) {
; #pragma unroll
;                 for (int ks = 0; ks < 4; ++ks) kf[ks] = kn[ks];
.LBB0_418:
	v_add_u32_e32 v95, s1, v118
	ds_read_b128 v[2:5], v95
	ds_read_b128 v[70:73], v95 offset:32
	ds_read_b128 v[78:81], v95 offset:64
	ds_read_b128 v[86:89], v95 offset:96
	v_add_u32_e32 v96, s1, v135
	s_waitcnt lgkmcnt(3)
	v_mfma_f32_32x32x16_bf16 v[2:17], v[66:69], v[2:5], 0
	ds_read_b32 v94, v96
	s_waitcnt lgkmcnt(0)
	s_addk_i32 s1, 0x100
	s_cmpk_lg_i32 s1, 0x400
	s_waitcnt lgkmcnt(3)
	v_mfma_f32_32x32x16_bf16 v[2:17], v[74:77], v[70:73], v[2:17]
	s_waitcnt lgkmcnt(2)
	v_mfma_f32_32x32x16_bf16 v[2:17], v[82:85], v[78:81], v[2:17]
	s_waitcnt lgkmcnt(1)
	v_mfma_f32_32x32x16_bf16 v[2:17], v[90:93], v[86:89], v[2:17]
	s_nop 11
	v_max_f32_e32 v2, 0, v2
	v_max_f32_e32 v3, 0, v3
	s_waitcnt lgkmcnt(0)
	v_fmac_f32_e32 v32, v94, v2
	v_fmac_f32_e32 v33, v94, v3
	v_max_f32_e32 v2, 0, v4
	v_max_f32_e32 v3, 0, v5
	v_fmac_f32_e32 v30, v94, v2
	v_fmac_f32_e32 v31, v94, v3
	v_max_f32_e32 v2, 0, v6
	v_max_f32_e32 v3, 0, v7
	v_fmac_f32_e32 v28, v94, v2
	v_fmac_f32_e32 v29, v94, v3
	v_max_f32_e32 v2, 0, v8
	v_max_f32_e32 v3, 0, v9
	v_fmac_f32_e32 v26, v94, v2
	v_fmac_f32_e32 v27, v94, v3
	v_max_f32_e32 v2, 0, v10
	v_max_f32_e32 v3, 0, v11
	v_fmac_f32_e32 v24, v94, v2
	v_fmac_f32_e32 v25, v94, v3
	v_max_f32_e32 v2, 0, v12
	v_max_f32_e32 v3, 0, v13
	v_fmac_f32_e32 v22, v94, v2
	v_fmac_f32_e32 v23, v94, v3
	v_max_f32_e32 v2, 0, v14
	v_max_f32_e32 v3, 0, v15
	v_fmac_f32_e32 v20, v94, v2
	v_fmac_f32_e32 v21, v94, v3
	v_max_f32_e32 v2, 0, v16
	v_max_f32_e32 v3, 0, v17
	v_fmac_f32_e32 v18, v94, v2
	v_fmac_f32_e32 v19, v94, v3
	ds_read_b128 v[2:5], v95 offset:128
	ds_read_b128 v[70:73], v95 offset:160
	ds_read_b128 v[78:81], v95 offset:192
	ds_read_b128 v[86:89], v95 offset:224
	ds_read_b32 v94, v96 offset:128
	s_waitcnt lgkmcnt(4)
	v_mfma_f32_32x32x16_bf16 v[2:17], v[66:69], v[2:5], 0
	s_waitcnt lgkmcnt(0)
	s_waitcnt lgkmcnt(3)
	v_mfma_f32_32x32x16_bf16 v[2:17], v[74:77], v[70:73], v[2:17]
	s_waitcnt lgkmcnt(2)
	v_mfma_f32_32x32x16_bf16 v[2:17], v[82:85], v[78:81], v[2:17]
	s_waitcnt lgkmcnt(1)
	v_mfma_f32_32x32x16_bf16 v[2:17], v[90:93], v[86:89], v[2:17]
	s_nop 11
	v_max_f32_e32 v2, 0, v2
	v_max_f32_e32 v3, 0, v3
	s_waitcnt lgkmcnt(0)
	v_fmac_f32_e32 v32, v94, v2
	v_fmac_f32_e32 v33, v94, v3
	v_max_f32_e32 v2, 0, v4
	v_max_f32_e32 v3, 0, v5
	v_fmac_f32_e32 v30, v94, v2
	v_fmac_f32_e32 v31, v94, v3
	v_max_f32_e32 v2, 0, v6
	v_max_f32_e32 v3, 0, v7
	v_fmac_f32_e32 v28, v94, v2
	v_fmac_f32_e32 v29, v94, v3
	v_max_f32_e32 v2, 0, v8
	v_max_f32_e32 v3, 0, v9
	v_fmac_f32_e32 v26, v94, v2
	v_fmac_f32_e32 v27, v94, v3
	v_max_f32_e32 v2, 0, v10
	v_max_f32_e32 v3, 0, v11
	v_fmac_f32_e32 v24, v94, v2
	v_fmac_f32_e32 v25, v94, v3
	v_max_f32_e32 v2, 0, v12
	v_max_f32_e32 v3, 0, v13
	v_fmac_f32_e32 v22, v94, v2
	v_fmac_f32_e32 v23, v94, v3
	v_max_f32_e32 v2, 0, v14
	v_max_f32_e32 v3, 0, v15
	v_fmac_f32_e32 v20, v94, v2
	v_fmac_f32_e32 v21, v94, v3
	v_max_f32_e32 v2, 0, v16
	v_max_f32_e32 v3, 0, v17
	v_fmac_f32_e32 v18, v94, v2
	v_fmac_f32_e32 v19, v94, v3
	s_cbranch_scc1 .LBB0_418
	v_or_b32_e32 v70, s0, v98
	v_or_b32_e32 v2, 3, v70
	v_or_b32_e32 v3, 2, v70
	v_cmp_le_i32_e64 s[92:93], v3, v0
	v_cmp_le_i32_e64 s[94:95], v2, v0
	v_or_b32_e32 v2, 5, v70
	v_or_b32_e32 v3, 4, v70
	v_cmp_le_i32_e64 s[84:85], v3, v0
	v_cmp_le_i32_e64 s[86:87], v2, v0
	v_or_b32_e32 v2, 7, v70
	v_or_b32_e32 v3, 6, v70
	v_cmp_le_i32_e64 s[76:77], v3, v0
	v_cmp_le_i32_e64 s[78:79], v2, v0
	v_or_b32_e32 v2, 17, v70
	v_or_b32_e32 v3, 16, v70
	v_cmp_le_i32_e64 s[68:69], v3, v0
	v_cmp_le_i32_e64 s[70:71], v2, v0
	v_or_b32_e32 v2, 19, v70
	v_or_b32_e32 v3, 18, v70
	v_cmp_le_i32_e64 s[60:61], v3, v0
	v_cmp_le_i32_e64 s[62:63], v2, v0
	v_or_b32_e32 v2, 21, v70
	v_or_b32_e32 v3, 20, v70
	v_pk_add_f32 v[16:17], v[32:33], 0 op_sel_hi:[1,0]
	v_cmp_le_i32_e64 s[8:9], v70, v0
	v_cmp_lt_i32_e64 s[4:5], v70, v0
	v_pk_add_f32 v[14:15], v[30:31], 0 op_sel_hi:[1,0]
	v_pk_add_f32 v[12:13], v[28:29], 0 op_sel_hi:[1,0]
	v_pk_add_f32 v[10:11], v[26:27], 0 op_sel_hi:[1,0]
	v_pk_add_f32 v[8:9], v[24:25], 0 op_sel_hi:[1,0]
	v_pk_add_f32 v[6:7], v[22:23], 0 op_sel_hi:[1,0]
	v_pk_add_f32 v[4:5], v[20:21], 0 op_sel_hi:[1,0]
	v_cmp_le_i32_e64 s[52:53], v3, v0
	v_cmp_le_i32_e64 s[54:55], v2, v0
	v_pk_add_f32 v[2:3], v[18:19], 0 op_sel_hi:[1,0]
	v_or_b32_e32 v18, 23, v70
	v_or_b32_e32 v19, 22, v70
	v_mov_b64_e32 v[72:73], v[68:69]
	v_mov_b64_e32 v[80:81], v[76:77]
	v_mov_b64_e32 v[88:89], v[84:85]
	v_mov_b64_e32 v[96:97], v[92:93]
	v_cmp_gt_i32_e64 s[96:97], 0, v17
	v_cmp_gt_i32_e64 s[6:7], 0, v16
	v_cmp_gt_i32_e64 s[90:91], 0, v14
	v_cmp_gt_i32_e64 s[46:47], 0, v15
	v_cmp_gt_i32_e64 s[82:83], 0, v12
	v_cmp_gt_i32_e64 s[88:89], 0, v13
	v_cmp_gt_i32_e64 s[74:75], 0, v10
	v_cmp_gt_i32_e64 s[80:81], 0, v11
	v_cmp_gt_i32_e64 s[66:67], 0, v8
	v_cmp_gt_i32_e64 s[72:73], 0, v9
	v_cmp_gt_i32_e64 s[58:59], 0, v6
	v_cmp_gt_i32_e64 s[64:65], 0, v7
	v_cmp_gt_i32_e64 s[50:51], 0, v4
	v_cmp_gt_i32_e64 s[56:57], 0, v5
	v_cmp_gt_i32_e64 s[0:1], 0, v2
	v_cmp_gt_i32_e64 s[48:49], 0, v3
	v_cmp_le_i32_e64 s[42:43], v19, v0
	v_cmp_le_i32_e64 s[44:45], v18, v0
	s_andn2_b64 vcc, exec, s[40:41]
	v_mov_b64_e32 v[70:71], v[66:67]
	v_mov_b64_e32 v[78:79], v[74:75]
	v_mov_b64_e32 v[86:87], v[82:83]
	v_mov_b64_e32 v[94:95], v[90:91]
	s_cbranch_vccnz .LBB0_421
	s_waitcnt vmcnt(3)
	v_mov_b64_e32 v[72:73], v[36:37]
	s_waitcnt vmcnt(2)
	v_mov_b64_e32 v[80:81], v[40:41]
	s_waitcnt vmcnt(1)
	v_mov_b64_e32 v[88:89], v[44:45]
	s_waitcnt vmcnt(0)
	v_mov_b64_e32 v[96:97], v[48:49]
	v_mov_b64_e32 v[70:71], v[34:35]
	v_mov_b64_e32 v[78:79], v[38:39]
	v_mov_b64_e32 v[86:87], v[42:43]
	v_mov_b64_e32 v[94:95], v[46:47]

; #define MFMA32(a, b, c) __builtin_amdgcn_mfma_f32_32x32x16_bf16((a), (b), (c), 0, 0, 0)
; DI void a1_task(unsigned char* shm, const bf16_t* prm, const bf16_t* prt, unsigned* mask, int b, int qt, const int tid) {
;     ...
;             for (int hh = 0; hh < 8; ++hh) {
;                 bf16x8 qa[4];
; #pragma unroll
;                 for (int ks = 0; ks < 4; ++ks) qa[ks] = *(const bf16x8*)(qb0 + hh * 128 + 32 * ks);
;                 const float wv = wqs[hh * 32 + r];
;                 asm volatile("s_waitcnt lgkmcnt(0)" ::: "memory");
;                 f32x16 acc;
; #pragma unroll
;                 for (int i = 0; i < 16; ++i) acc[i] = 0.f;
; #pragma unroll
;                 for (int ks = 0; ks < 4; ++ks) acc = MFMA32(kf[ks], qa[ks], acc);
; #pragma unroll
;                 for (int i = 0; i < 16; ++i) idx[i] = fmaf(wv, fmaxf(acc[i], 0.f), idx[i]);
;             }
; #pragma unroll
;             for (int i = 0; i < 16; ++i) {
;                 const int s = s0 + 16 * (i >> 3) + 8 * h + (i & 7);
;                 const unsigned u = __float_as_uint(idx[i] + 0.0f);
;                 const unsigned k = (u & 0x80000000u) ? ~u : (u | 0x80000000u);
;                 key[jt][i] = (s <= t0 + r) ? k : 0u;
;             }
;             if (hn) {
; #pragma unroll
;                 for (int ks = 0; ks < 4; ++ks) kf[ks] = kn[ks];
.LBB0_428:
	v_add_u32_e32 v91, s1, v118
	ds_read_b128 v[2:5], v91
	ds_read_b128 v[66:69], v91 offset:32
	ds_read_b128 v[74:77], v91 offset:64
	ds_read_b128 v[82:85], v91 offset:96
	v_add_u32_e32 v92, s1, v135
	s_waitcnt lgkmcnt(3)
	v_mfma_f32_32x32x16_bf16 v[2:17], v[70:73], v[2:5], 0
	ds_read_b32 v90, v92
	s_waitcnt lgkmcnt(0)
	s_addk_i32 s1, 0x100
	s_cmpk_lg_i32 s1, 0x400
	s_waitcnt lgkmcnt(3)
	v_mfma_f32_32x32x16_bf16 v[2:17], v[78:81], v[66:69], v[2:17]
	s_waitcnt lgkmcnt(2)
	v_mfma_f32_32x32x16_bf16 v[2:17], v[86:89], v[74:77], v[2:17]
	s_waitcnt lgkmcnt(1)
	v_mfma_f32_32x32x16_bf16 v[2:17], v[94:97], v[82:85], v[2:17]
	s_nop 11
	v_max_f32_e32 v2, 0, v2
	v_max_f32_e32 v3, 0, v3
	s_waitcnt lgkmcnt(0)
	v_fmac_f32_e32 v64, v90, v2
	v_fmac_f32_e32 v65, v90, v3
	v_max_f32_e32 v2, 0, v4
	v_max_f32_e32 v3, 0, v5
	v_fmac_f32_e32 v62, v90, v2
	v_fmac_f32_e32 v63, v90, v3
	v_max_f32_e32 v2, 0, v6
	v_max_f32_e32 v3, 0, v7
	v_fmac_f32_e32 v60, v90, v2
	v_fmac_f32_e32 v61, v90, v3
	v_max_f32_e32 v2, 0, v8
	v_max_f32_e32 v3, 0, v9
	v_fmac_f32_e32 v58, v90, v2
	v_fmac_f32_e32 v59, v90, v3
	v_max_f32_e32 v2, 0, v10
	v_max_f32_e32 v3, 0, v11
	v_fmac_f32_e32 v56, v90, v2
	v_fmac_f32_e32 v57, v90, v3
	v_max_f32_e32 v2, 0, v12
	v_max_f32_e32 v3, 0, v13
	v_fmac_f32_e32 v54, v90, v2
	v_fmac_f32_e32 v55, v90, v3
	v_max_f32_e32 v2, 0, v14
	v_max_f32_e32 v3, 0, v15
	v_fmac_f32_e32 v52, v90, v2
	v_fmac_f32_e32 v53, v90, v3
	v_max_f32_e32 v2, 0, v16
	v_max_f32_e32 v3, 0, v17
	v_fmac_f32_e32 v50, v90, v2
	v_fmac_f32_e32 v51, v90, v3
	ds_read_b128 v[2:5], v91 offset:128
	ds_read_b128 v[66:69], v91 offset:160
	ds_read_b128 v[74:77], v91 offset:192
	ds_read_b128 v[82:85], v91 offset:224
	ds_read_b32 v90, v92 offset:128
	s_waitcnt lgkmcnt(4)
	v_mfma_f32_32x32x16_bf16 v[2:17], v[70:73], v[2:5], 0
	s_waitcnt lgkmcnt(0)
	s_waitcnt lgkmcnt(3)
	v_mfma_f32_32x32x16_bf16 v[2:17], v[78:81], v[66:69], v[2:17]
	s_waitcnt lgkmcnt(2)
	v_mfma_f32_32x32x16_bf16 v[2:17], v[86:89], v[74:77], v[2:17]
	s_waitcnt lgkmcnt(1)
	v_mfma_f32_32x32x16_bf16 v[2:17], v[94:97], v[82:85], v[2:17]
	s_nop 11
	v_max_f32_e32 v2, 0, v2
	v_max_f32_e32 v3, 0, v3
	s_waitcnt lgkmcnt(0)
	v_fmac_f32_e32 v64, v90, v2
	v_fmac_f32_e32 v65, v90, v3
	v_max_f32_e32 v2, 0, v4
	v_max_f32_e32 v3, 0, v5
	v_fmac_f32_e32 v62, v90, v2
	v_fmac_f32_e32 v63, v90, v3
	v_max_f32_e32 v2, 0, v6
	v_max_f32_e32 v3, 0, v7
	v_fmac_f32_e32 v60, v90, v2
	v_fmac_f32_e32 v61, v90, v3
	v_max_f32_e32 v2, 0, v8
	v_max_f32_e32 v3, 0, v9
	v_fmac_f32_e32 v58, v90, v2
	v_fmac_f32_e32 v59, v90, v3
	v_max_f32_e32 v2, 0, v10
	v_max_f32_e32 v3, 0, v11
	v_fmac_f32_e32 v56, v90, v2
	v_fmac_f32_e32 v57, v90, v3
	v_max_f32_e32 v2, 0, v12
	v_max_f32_e32 v3, 0, v13
	v_fmac_f32_e32 v54, v90, v2
	v_fmac_f32_e32 v55, v90, v3
	v_max_f32_e32 v2, 0, v14
	v_max_f32_e32 v3, 0, v15
	v_fmac_f32_e32 v52, v90, v2
	v_fmac_f32_e32 v53, v90, v3
	v_max_f32_e32 v2, 0, v16
	v_max_f32_e32 v3, 0, v17
	v_fmac_f32_e32 v50, v90, v2
	v_fmac_f32_e32 v51, v90, v3
	s_cbranch_scc1 .LBB0_428
	v_or_b32_e32 v66, s0, v98
	v_or_b32_e32 v2, 3, v66
	v_or_b32_e32 v3, 2, v66
	v_cmp_le_i32_e64 s[92:93], v3, v0
	v_cmp_le_i32_e64 s[94:95], v2, v0
	v_or_b32_e32 v2, 5, v66
	v_or_b32_e32 v3, 4, v66
	v_cmp_le_i32_e64 s[84:85], v3, v0
	v_cmp_le_i32_e64 s[86:87], v2, v0
	v_or_b32_e32 v2, 7, v66
	v_or_b32_e32 v3, 6, v66
	v_cmp_le_i32_e64 s[76:77], v3, v0
	v_cmp_le_i32_e64 s[78:79], v2, v0
	v_or_b32_e32 v2, 17, v66
	v_or_b32_e32 v3, 16, v66
	v_cmp_le_i32_e64 s[68:69], v3, v0
	v_cmp_le_i32_e64 s[70:71], v2, v0
	v_or_b32_e32 v2, 19, v66
	v_or_b32_e32 v3, 18, v66
	v_cmp_le_i32_e64 s[60:61], v3, v0
	v_cmp_le_i32_e64 s[62:63], v2, v0
	v_or_b32_e32 v2, 21, v66
	v_or_b32_e32 v3, 20, v66
	v_cmp_le_i32_e64 s[52:53], v3, v0
	v_cmp_le_i32_e64 s[54:55], v2, v0
	v_pk_add_f32 v[2:3], v[50:51], 0 op_sel_hi:[1,0]
	v_or_b32_e32 v50, 23, v66
	v_or_b32_e32 v51, 22, v66
	v_pk_add_f32 v[16:17], v[64:65], 0 op_sel_hi:[1,0]
	v_pk_add_f32 v[14:15], v[62:63], 0 op_sel_hi:[1,0]
	v_pk_add_f32 v[12:13], v[60:61], 0 op_sel_hi:[1,0]
	v_pk_add_f32 v[10:11], v[58:59], 0 op_sel_hi:[1,0]
	v_pk_add_f32 v[8:9], v[56:57], 0 op_sel_hi:[1,0]
	v_pk_add_f32 v[6:7], v[54:55], 0 op_sel_hi:[1,0]
	v_pk_add_f32 v[4:5], v[52:53], 0 op_sel_hi:[1,0]
	v_cmp_le_i32_e64 s[42:43], v51, v0
	v_cmp_le_i32_e64 s[44:45], v50, v0
	v_mov_b64_e32 v[50:51], v[70:71]
	v_mov_b64_e32 v[54:55], v[78:79]
	v_mov_b64_e32 v[58:59], v[86:87]
	v_mov_b64_e32 v[62:63], v[94:95]
	v_cmp_gt_i32_e64 s[96:97], 0, v17
	v_cmp_gt_i32_e64 s[6:7], 0, v16
	v_cmp_le_i32_e64 s[8:9], v66, v0
	v_cmp_lt_i32_e64 s[4:5], v66, v0
	v_cmp_gt_i32_e64 s[90:91], 0, v14
	v_cmp_gt_i32_e64 s[46:47], 0, v15
	v_cmp_gt_i32_e64 s[82:83], 0, v12
	v_cmp_gt_i32_e64 s[88:89], 0, v13
	v_cmp_gt_i32_e64 s[74:75], 0, v10
	v_cmp_gt_i32_e64 s[80:81], 0, v11
	v_cmp_gt_i32_e64 s[66:67], 0, v8
	v_cmp_gt_i32_e64 s[72:73], 0, v9
	v_cmp_gt_i32_e64 s[58:59], 0, v6
	v_cmp_gt_i32_e64 s[64:65], 0, v7
	v_cmp_gt_i32_e64 s[50:51], 0, v4
	v_cmp_gt_i32_e64 s[56:57], 0, v5
	v_cmp_gt_i32_e64 s[0:1], 0, v2
	v_cmp_gt_i32_e64 s[48:49], 0, v3
	s_andn2_b64 vcc, exec, s[40:41]
	v_mov_b64_e32 v[52:53], v[72:73]
	v_mov_b64_e32 v[56:57], v[80:81]
	v_mov_b64_e32 v[60:61], v[88:89]
	v_mov_b64_e32 v[64:65], v[96:97]
	s_cbranch_vccnz .LBB0_431
	s_waitcnt vmcnt(3)
	v_mov_b64_e32 v[52:53], v[20:21]
	s_waitcnt vmcnt(2)
	v_mov_b64_e32 v[56:57], v[24:25]
	s_waitcnt vmcnt(1)
	v_mov_b64_e32 v[60:61], v[28:29]
	s_waitcnt vmcnt(0)
	v_mov_b64_e32 v[64:65], v[32:33]
	v_mov_b64_e32 v[50:51], v[18:19]
	v_mov_b64_e32 v[54:55], v[22:23]
	v_mov_b64_e32 v[58:59], v[26:27]
	v_mov_b64_e32 v[62:63], v[30:31]

; #define MFMA32(a, b, c) __builtin_amdgcn_mfma_f32_32x32x16_bf16((a), (b), (c), 0, 0, 0)
; DI void a1_task(unsigned char* shm, const bf16_t* prm, const bf16_t* prt, unsigned* mask, int b, int qt, const int tid) {
;     ...
;             for (int hh = 0; hh < 8; ++hh) {
;                 bf16x8 qa[4];
; #pragma unroll
;                 for (int ks = 0; ks < 4; ++ks) qa[ks] = *(const bf16x8*)(qb0 + hh * 128 + 32 * ks);
;                 const float wv = wqs[hh * 32 + r];
;                 asm volatile("s_waitcnt lgkmcnt(0)" ::: "memory");
;                 f32x16 acc;
; #pragma unroll
;                 for (int i = 0; i < 16; ++i) acc[i] = 0.f;
; #pragma unroll
;                 for (int ks = 0; ks < 4; ++ks) acc = MFMA32(kf[ks], qa[ks], acc);
; #pragma unroll
;                 for (int i = 0; i < 16; ++i) idx[i] = fmaf(wv, fmaxf(acc[i], 0.f), idx[i]);
;             }
; #pragma unroll
;             for (int i = 0; i < 16; ++i) {
;                 const int s = s0 + 16 * (i >> 3) + 8 * h + (i & 7);
;                 const unsigned u = __float_as_uint(idx[i] + 0.0f);
;                 const unsigned k = (u & 0x80000000u) ? ~u : (u | 0x80000000u);
;                 key[jt][i] = (s <= t0 + r) ? k : 0u;
;             }
;             if (hn) {
; #pragma unroll
;                 for (int ks = 0; ks < 4; ++ks) kf[ks] = kn[ks];
.LBB0_438:
	v_add_u32_e32 v199, s1, v118
	ds_read_b128 v[2:5], v199
	ds_read_b128 v[86:89], v199 offset:32
	ds_read_b128 v[94:97], v199 offset:64
	ds_read_b128 v[244:247], v199 offset:96
	v_add_u32_e32 v200, s1, v135
	s_waitcnt lgkmcnt(3)
	v_mfma_f32_32x32x16_bf16 v[2:17], v[50:53], v[2:5], 0
	ds_read_b32 v198, v200
	s_waitcnt lgkmcnt(0)
	s_addk_i32 s1, 0x100
	s_cmpk_lg_i32 s1, 0x400
	s_waitcnt lgkmcnt(3)
	v_mfma_f32_32x32x16_bf16 v[2:17], v[54:57], v[86:89], v[2:17]
	s_waitcnt lgkmcnt(2)
	v_mfma_f32_32x32x16_bf16 v[2:17], v[58:61], v[94:97], v[2:17]
	s_waitcnt lgkmcnt(1)
	v_mfma_f32_32x32x16_bf16 v[2:17], v[62:65], v[244:247], v[2:17]
	s_nop 11
	v_max_f32_e32 v2, 0, v2
	v_max_f32_e32 v3, 0, v3
	s_waitcnt lgkmcnt(0)
	v_fmac_f32_e32 v80, v198, v2
	v_fmac_f32_e32 v81, v198, v3
	v_max_f32_e32 v2, 0, v4
	v_max_f32_e32 v3, 0, v5
	v_fmac_f32_e32 v78, v198, v2
	v_fmac_f32_e32 v79, v198, v3
	v_max_f32_e32 v2, 0, v6
	v_max_f32_e32 v3, 0, v7
	v_fmac_f32_e32 v76, v198, v2
	v_fmac_f32_e32 v77, v198, v3
	v_max_f32_e32 v2, 0, v8
	v_max_f32_e32 v3, 0, v9
	v_fmac_f32_e32 v74, v198, v2
	v_fmac_f32_e32 v75, v198, v3
	v_max_f32_e32 v2, 0, v10
	v_max_f32_e32 v3, 0, v11
	v_fmac_f32_e32 v72, v198, v2
	v_fmac_f32_e32 v73, v198, v3
	v_max_f32_e32 v2, 0, v12
	v_max_f32_e32 v3, 0, v13
	v_fmac_f32_e32 v70, v198, v2
	v_fmac_f32_e32 v71, v198, v3
	v_max_f32_e32 v2, 0, v14
	v_max_f32_e32 v3, 0, v15
	v_fmac_f32_e32 v68, v198, v2
	v_fmac_f32_e32 v69, v198, v3
	v_max_f32_e32 v2, 0, v16
	v_max_f32_e32 v3, 0, v17
	v_fmac_f32_e32 v66, v198, v2
	v_fmac_f32_e32 v67, v198, v3
	ds_read_b128 v[2:5], v199 offset:128
	ds_read_b128 v[86:89], v199 offset:160
	ds_read_b128 v[94:97], v199 offset:192
	ds_read_b128 v[244:247], v199 offset:224
	ds_read_b32 v198, v200 offset:128
	s_waitcnt lgkmcnt(4)
	v_mfma_f32_32x32x16_bf16 v[2:17], v[50:53], v[2:5], 0
	s_waitcnt lgkmcnt(0)
	s_waitcnt lgkmcnt(3)
	v_mfma_f32_32x32x16_bf16 v[2:17], v[54:57], v[86:89], v[2:17]
	s_waitcnt lgkmcnt(2)
	v_mfma_f32_32x32x16_bf16 v[2:17], v[58:61], v[94:97], v[2:17]
	s_waitcnt lgkmcnt(1)
	v_mfma_f32_32x32x16_bf16 v[2:17], v[62:65], v[244:247], v[2:17]
	s_nop 11
	v_max_f32_e32 v2, 0, v2
	v_max_f32_e32 v3, 0, v3
	s_waitcnt lgkmcnt(0)
	v_fmac_f32_e32 v80, v198, v2
	v_fmac_f32_e32 v81, v198, v3
	v_max_f32_e32 v2, 0, v4
	v_max_f32_e32 v3, 0, v5
	v_fmac_f32_e32 v78, v198, v2
	v_fmac_f32_e32 v79, v198, v3
	v_max_f32_e32 v2, 0, v6
	v_max_f32_e32 v3, 0, v7
	v_fmac_f32_e32 v76, v198, v2
	v_fmac_f32_e32 v77, v198, v3
	v_max_f32_e32 v2, 0, v8
	v_max_f32_e32 v3, 0, v9
	v_fmac_f32_e32 v74, v198, v2
	v_fmac_f32_e32 v75, v198, v3
	v_max_f32_e32 v2, 0, v10
	v_max_f32_e32 v3, 0, v11
	v_fmac_f32_e32 v72, v198, v2
	v_fmac_f32_e32 v73, v198, v3
	v_max_f32_e32 v2, 0, v12
	v_max_f32_e32 v3, 0, v13
	v_fmac_f32_e32 v70, v198, v2
	v_fmac_f32_e32 v71, v198, v3
	v_max_f32_e32 v2, 0, v14
	v_max_f32_e32 v3, 0, v15
	v_fmac_f32_e32 v68, v198, v2
	v_fmac_f32_e32 v69, v198, v3
	v_max_f32_e32 v2, 0, v16
	v_max_f32_e32 v3, 0, v17
	v_fmac_f32_e32 v66, v198, v2
	v_fmac_f32_e32 v67, v198, v3
	s_cbranch_scc1 .LBB0_438
	v_or_b32_e32 v86, s0, v98
	v_or_b32_e32 v2, 3, v86
	v_or_b32_e32 v3, 2, v86
	v_cmp_le_i32_e64 s[92:93], v3, v0
	v_cmp_le_i32_e64 s[94:95], v2, v0
	v_or_b32_e32 v2, 5, v86
	v_or_b32_e32 v3, 4, v86
	v_cmp_le_i32_e64 s[84:85], v3, v0
	v_cmp_le_i32_e64 s[86:87], v2, v0
	v_or_b32_e32 v2, 7, v86
	v_or_b32_e32 v3, 6, v86
	v_cmp_le_i32_e64 s[76:77], v3, v0
	v_cmp_le_i32_e64 s[78:79], v2, v0
	v_or_b32_e32 v2, 17, v86
	v_or_b32_e32 v3, 16, v86
	v_cmp_le_i32_e64 s[68:69], v3, v0
	v_cmp_le_i32_e64 s[70:71], v2, v0
	v_or_b32_e32 v2, 19, v86
	v_or_b32_e32 v3, 18, v86
	v_cmp_le_i32_e64 s[60:61], v3, v0
	v_cmp_le_i32_e64 s[62:63], v2, v0
	v_or_b32_e32 v2, 21, v86
	v_or_b32_e32 v3, 20, v86
	v_cmp_le_i32_e64 s[52:53], v3, v0
	v_cmp_le_i32_e64 s[54:55], v2, v0
	v_pk_add_f32 v[2:3], v[66:67], 0 op_sel_hi:[1,0]
	v_or_b32_e32 v66, 23, v86
	v_or_b32_e32 v67, 22, v86
	v_pk_add_f32 v[16:17], v[80:81], 0 op_sel_hi:[1,0]
	v_pk_add_f32 v[14:15], v[78:79], 0 op_sel_hi:[1,0]
	v_pk_add_f32 v[12:13], v[76:77], 0 op_sel_hi:[1,0]
	v_pk_add_f32 v[10:11], v[74:75], 0 op_sel_hi:[1,0]
	v_pk_add_f32 v[8:9], v[72:73], 0 op_sel_hi:[1,0]
	v_pk_add_f32 v[6:7], v[70:71], 0 op_sel_hi:[1,0]
	v_pk_add_f32 v[4:5], v[68:69], 0 op_sel_hi:[1,0]
	v_cmp_le_i32_e64 s[42:43], v67, v0
	v_cmp_le_i32_e64 s[44:45], v66, v0
	v_mov_b64_e32 v[68:69], v[52:53]
	v_mov_b64_e32 v[72:73], v[56:57]
	v_mov_b64_e32 v[76:77], v[60:61]
	v_mov_b64_e32 v[80:81], v[64:65]
	v_cmp_gt_i32_e64 s[96:97], 0, v17
	v_cmp_gt_i32_e64 s[6:7], 0, v16
	v_cmp_le_i32_e64 s[8:9], v86, v0
	v_cmp_lt_i32_e64 s[4:5], v86, v0
	v_cmp_gt_i32_e64 s[90:91], 0, v14
	v_cmp_gt_i32_e64 s[46:47], 0, v15
	v_cmp_gt_i32_e64 s[82:83], 0, v12
	v_cmp_gt_i32_e64 s[88:89], 0, v13
	v_cmp_gt_i32_e64 s[74:75], 0, v10
	v_cmp_gt_i32_e64 s[80:81], 0, v11
	v_cmp_gt_i32_e64 s[66:67], 0, v8
	v_cmp_gt_i32_e64 s[72:73], 0, v9
	v_cmp_gt_i32_e64 s[58:59], 0, v6
	v_cmp_gt_i32_e64 s[64:65], 0, v7
	v_cmp_gt_i32_e64 s[50:51], 0, v4
	v_cmp_gt_i32_e64 s[56:57], 0, v5
	v_cmp_gt_i32_e64 s[0:1], 0, v2
	v_cmp_gt_i32_e64 s[48:49], 0, v3
	s_andn2_b64 vcc, exec, s[40:41]
	v_mov_b64_e32 v[66:67], v[50:51]
	v_mov_b64_e32 v[70:71], v[54:55]
	v_mov_b64_e32 v[74:75], v[58:59]
	v_mov_b64_e32 v[78:79], v[62:63]
	s_cbranch_vccnz .LBB0_441
	s_waitcnt vmcnt(3)
	v_mov_b64_e32 v[68:69], v[48:49]
	s_waitcnt vmcnt(2)
	v_mov_b64_e32 v[72:73], v[44:45]
	s_waitcnt vmcnt(1)
	v_mov_b64_e32 v[76:77], v[40:41]
	s_waitcnt vmcnt(0)
	v_mov_b64_e32 v[80:81], v[36:37]
	v_mov_b64_e32 v[66:67], v[46:47]
	v_mov_b64_e32 v[70:71], v[42:43]
	v_mov_b64_e32 v[74:75], v[38:39]
	v_mov_b64_e32 v[78:79], v[34:35]

; #define MFMA32(a, b, c) __builtin_amdgcn_mfma_f32_32x32x16_bf16((a), (b), (c), 0, 0, 0)
; DI void a1_task(unsigned char* shm, const bf16_t* prm, const bf16_t* prt, unsigned* mask, int b, int qt, const int tid) {
;     ...
;             for (int hh = 0; hh < 8; ++hh) {
;                 bf16x8 qa[4];
; #pragma unroll
;                 for (int ks = 0; ks < 4; ++ks) qa[ks] = *(const bf16x8*)(qb0 + hh * 128 + 32 * ks);
;                 const float wv = wqs[hh * 32 + r];
;                 asm volatile("s_waitcnt lgkmcnt(0)" ::: "memory");
;                 f32x16 acc;
; #pragma unroll
;                 for (int i = 0; i < 16; ++i) acc[i] = 0.f;
; #pragma unroll
;                 for (int ks = 0; ks < 4; ++ks) acc = MFMA32(kf[ks], qa[ks], acc);
; #pragma unroll
;                 for (int i = 0; i < 16; ++i) idx[i] = fmaf(wv, fmaxf(acc[i], 0.f), idx[i]);
;             }
; #pragma unroll
;             for (int i = 0; i < 16; ++i) {
;                 const int s = s0 + 16 * (i >> 3) + 8 * h + (i & 7);
;                 const unsigned u = __float_as_uint(idx[i] + 0.0f);
;                 const unsigned k = (u & 0x80000000u) ? ~u : (u | 0x80000000u);
;                 key[jt][i] = (s <= t0 + r) ? k : 0u;
;             }
;             if (hn) {
; #pragma unroll
;                 for (int ks = 0; ks < 4; ++ks) kf[ks] = kn[ks];
.LBB0_448:
	v_add_u32_e32 v63, s1, v118
	ds_read_b128 v[2:5], v63
	ds_read_b128 v[50:53], v63 offset:32
	ds_read_b128 v[54:57], v63 offset:64
	ds_read_b128 v[58:61], v63 offset:96
	v_add_u32_e32 v64, s1, v135
	s_waitcnt lgkmcnt(3)
	v_mfma_f32_32x32x16_bf16 v[2:17], v[66:69], v[2:5], 0
	ds_read_b32 v62, v64
	s_waitcnt lgkmcnt(0)
	s_addk_i32 s1, 0x100
	s_cmpk_lg_i32 s1, 0x400
	s_waitcnt lgkmcnt(3)
	v_mfma_f32_32x32x16_bf16 v[2:17], v[70:73], v[50:53], v[2:17]
	s_waitcnt lgkmcnt(2)
	v_mfma_f32_32x32x16_bf16 v[2:17], v[74:77], v[54:57], v[2:17]
	s_waitcnt lgkmcnt(1)
	v_mfma_f32_32x32x16_bf16 v[2:17], v[78:81], v[58:61], v[2:17]
	s_nop 11
	v_max_f32_e32 v2, 0, v2
	v_max_f32_e32 v3, 0, v3
	s_waitcnt lgkmcnt(0)
	v_fmac_f32_e32 v32, v62, v2
	v_fmac_f32_e32 v33, v62, v3
	v_max_f32_e32 v2, 0, v4
	v_max_f32_e32 v3, 0, v5
	v_fmac_f32_e32 v30, v62, v2
	v_fmac_f32_e32 v31, v62, v3
	v_max_f32_e32 v2, 0, v6
	v_max_f32_e32 v3, 0, v7
	v_fmac_f32_e32 v28, v62, v2
	v_fmac_f32_e32 v29, v62, v3
	v_max_f32_e32 v2, 0, v8
	v_max_f32_e32 v3, 0, v9
	v_fmac_f32_e32 v26, v62, v2
	v_fmac_f32_e32 v27, v62, v3
	v_max_f32_e32 v2, 0, v10
	v_max_f32_e32 v3, 0, v11
	v_fmac_f32_e32 v24, v62, v2
	v_fmac_f32_e32 v25, v62, v3
	v_max_f32_e32 v2, 0, v12
	v_max_f32_e32 v3, 0, v13
	v_fmac_f32_e32 v22, v62, v2
	v_fmac_f32_e32 v23, v62, v3
	v_max_f32_e32 v2, 0, v14
	v_max_f32_e32 v3, 0, v15
	v_fmac_f32_e32 v20, v62, v2
	v_fmac_f32_e32 v21, v62, v3
	v_max_f32_e32 v2, 0, v16
	v_max_f32_e32 v3, 0, v17
	v_fmac_f32_e32 v18, v62, v2
	v_fmac_f32_e32 v19, v62, v3
	ds_read_b128 v[2:5], v63 offset:128
	ds_read_b128 v[50:53], v63 offset:160
	ds_read_b128 v[54:57], v63 offset:192
	ds_read_b128 v[58:61], v63 offset:224
	ds_read_b32 v62, v64 offset:128
	s_waitcnt lgkmcnt(4)
	v_mfma_f32_32x32x16_bf16 v[2:17], v[66:69], v[2:5], 0
	s_waitcnt lgkmcnt(0)
	s_waitcnt lgkmcnt(3)
	v_mfma_f32_32x32x16_bf16 v[2:17], v[70:73], v[50:53], v[2:17]
	s_waitcnt lgkmcnt(2)
	v_mfma_f32_32x32x16_bf16 v[2:17], v[74:77], v[54:57], v[2:17]
	s_waitcnt lgkmcnt(1)
	v_mfma_f32_32x32x16_bf16 v[2:17], v[78:81], v[58:61], v[2:17]
	s_nop 11
	v_max_f32_e32 v2, 0, v2
	v_max_f32_e32 v3, 0, v3
	s_waitcnt lgkmcnt(0)
	v_fmac_f32_e32 v32, v62, v2
	v_fmac_f32_e32 v33, v62, v3
	v_max_f32_e32 v2, 0, v4
	v_max_f32_e32 v3, 0, v5
	v_fmac_f32_e32 v30, v62, v2
	v_fmac_f32_e32 v31, v62, v3
	v_max_f32_e32 v2, 0, v6
	v_max_f32_e32 v3, 0, v7
	v_fmac_f32_e32 v28, v62, v2
	v_fmac_f32_e32 v29, v62, v3
	v_max_f32_e32 v2, 0, v8
	v_max_f32_e32 v3, 0, v9
	v_fmac_f32_e32 v26, v62, v2
	v_fmac_f32_e32 v27, v62, v3
	v_max_f32_e32 v2, 0, v10
	v_max_f32_e32 v3, 0, v11
	v_fmac_f32_e32 v24, v62, v2
	v_fmac_f32_e32 v25, v62, v3
	v_max_f32_e32 v2, 0, v12
	v_max_f32_e32 v3, 0, v13
	v_fmac_f32_e32 v22, v62, v2
	v_fmac_f32_e32 v23, v62, v3
	v_max_f32_e32 v2, 0, v14
	v_max_f32_e32 v3, 0, v15
	v_fmac_f32_e32 v20, v62, v2
	v_fmac_f32_e32 v21, v62, v3
	v_max_f32_e32 v2, 0, v16
	v_max_f32_e32 v3, 0, v17
	v_fmac_f32_e32 v18, v62, v2
	v_fmac_f32_e32 v19, v62, v3
	s_cbranch_scc1 .LBB0_448
	v_or_b32_e32 v50, s0, v98
	v_or_b32_e32 v2, 3, v50
	v_or_b32_e32 v3, 2, v50
	v_cmp_le_i32_e64 s[92:93], v3, v0
	v_cmp_le_i32_e64 s[94:95], v2, v0
	v_or_b32_e32 v2, 5, v50
	v_or_b32_e32 v3, 4, v50
	v_cmp_le_i32_e64 s[84:85], v3, v0
	v_cmp_le_i32_e64 s[86:87], v2, v0
	v_or_b32_e32 v2, 7, v50
	v_or_b32_e32 v3, 6, v50
	v_cmp_le_i32_e64 s[76:77], v3, v0
	v_cmp_le_i32_e64 s[78:79], v2, v0
	v_or_b32_e32 v2, 17, v50
	v_or_b32_e32 v3, 16, v50
	v_cmp_le_i32_e64 s[68:69], v3, v0
	v_cmp_le_i32_e64 s[70:71], v2, v0
	v_or_b32_e32 v2, 19, v50
	v_or_b32_e32 v3, 18, v50
	v_cmp_le_i32_e64 s[60:61], v3, v0
	v_cmp_le_i32_e64 s[62:63], v2, v0
	v_or_b32_e32 v2, 21, v50
	v_or_b32_e32 v3, 20, v50
	v_cmp_le_i32_e64 s[52:53], v3, v0
	v_cmp_le_i32_e64 s[54:55], v2, v0
	v_pk_add_f32 v[2:3], v[18:19], 0 op_sel_hi:[1,0]
	v_or_b32_e32 v18, 23, v50
	v_or_b32_e32 v19, 22, v50
	v_pk_add_f32 v[16:17], v[32:33], 0 op_sel_hi:[1,0]
	v_pk_add_f32 v[14:15], v[30:31], 0 op_sel_hi:[1,0]
	v_pk_add_f32 v[12:13], v[28:29], 0 op_sel_hi:[1,0]
	v_pk_add_f32 v[10:11], v[26:27], 0 op_sel_hi:[1,0]
	v_pk_add_f32 v[8:9], v[24:25], 0 op_sel_hi:[1,0]
	v_pk_add_f32 v[6:7], v[22:23], 0 op_sel_hi:[1,0]
	v_pk_add_f32 v[4:5], v[20:21], 0 op_sel_hi:[1,0]
	v_cmp_le_i32_e64 s[42:43], v19, v0
	v_cmp_le_i32_e64 s[44:45], v18, v0
	v_mov_b64_e32 v[18:19], v[66:67]
	v_mov_b64_e32 v[22:23], v[70:71]
	v_mov_b64_e32 v[26:27], v[74:75]
	v_mov_b64_e32 v[30:31], v[78:79]
	v_cmp_gt_i32_e64 s[96:97], 0, v17
	v_cmp_gt_i32_e64 s[6:7], 0, v16
	v_cmp_le_i32_e64 s[8:9], v50, v0
	v_cmp_lt_i32_e64 s[4:5], v50, v0
	v_cmp_gt_i32_e64 s[90:91], 0, v14
	v_cmp_gt_i32_e64 s[46:47], 0, v15
	v_cmp_gt_i32_e64 s[82:83], 0, v12
	v_cmp_gt_i32_e64 s[88:89], 0, v13
	v_cmp_gt_i32_e64 s[74:75], 0, v10
	v_cmp_gt_i32_e64 s[80:81], 0, v11
	v_cmp_gt_i32_e64 s[66:67], 0, v8
	v_cmp_gt_i32_e64 s[72:73], 0, v9
	v_cmp_gt_i32_e64 s[58:59], 0, v6
	v_cmp_gt_i32_e64 s[64:65], 0, v7
	v_cmp_gt_i32_e64 s[50:51], 0, v4
	v_cmp_gt_i32_e64 s[56:57], 0, v5
	v_cmp_gt_i32_e64 s[0:1], 0, v2
	v_cmp_gt_i32_e64 s[48:49], 0, v3
	s_andn2_b64 vcc, exec, vcc
	v_mov_b64_e32 v[20:21], v[68:69]
	v_mov_b64_e32 v[24:25], v[72:73]
	v_mov_b64_e32 v[28:29], v[76:77]
	v_mov_b64_e32 v[32:33], v[80:81]
	s_cbranch_vccnz .LBB0_451
	s_waitcnt vmcnt(0)
	v_mov_b64_e32 v[18:19], v[46:47]
	v_mov_b64_e32 v[22:23], v[42:43]
	v_mov_b64_e32 v[26:27], v[38:39]
	v_mov_b64_e32 v[30:31], v[34:35]
	v_mov_b64_e32 v[20:21], v[48:49]
	v_mov_b64_e32 v[24:25], v[44:45]
	v_mov_b64_e32 v[28:29], v[40:41]
	v_mov_b64_e32 v[32:33], v[36:37]

; #define MFMA32(a, b, c) __builtin_amdgcn_mfma_f32_32x32x16_bf16((a), (b), (c), 0, 0, 0)
; DI void a1_task(unsigned char* shm, const bf16_t* prm, const bf16_t* prt, unsigned* mask, int b, int qt, const int tid) {
;     ...
;             for (int hh = 0; hh < 8; ++hh) {
;                 bf16x8 qa[4];
; #pragma unroll
;                 for (int ks = 0; ks < 4; ++ks) qa[ks] = *(const bf16x8*)(qb0 + hh * 128 + 32 * ks);
;                 const float wv = wqs[hh * 32 + r];
;                 asm volatile("s_waitcnt lgkmcnt(0)" ::: "memory");
;                 f32x16 acc;
; #pragma unroll
;                 for (int i = 0; i < 16; ++i) acc[i] = 0.f;
; #pragma unroll
;                 for (int ks = 0; ks < 4; ++ks) acc = MFMA32(kf[ks], qa[ks], acc);
; #pragma unroll
;                 for (int i = 0; i < 16; ++i) idx[i] = fmaf(wv, fmaxf(acc[i], 0.f), idx[i]);
;             }
.LBB0_456:
	v_add_u32_e32 v79, s0, v118
	ds_read_b128 v[2:5], v79
	ds_read_b128 v[66:69], v79 offset:32
	ds_read_b128 v[70:73], v79 offset:64
	ds_read_b128 v[74:77], v79 offset:96
	v_add_u32_e32 v80, s0, v135
	s_waitcnt lgkmcnt(3)
	v_mfma_f32_32x32x16_bf16 v[2:17], v[18:21], v[2:5], 0
	ds_read_b32 v78, v80
	s_waitcnt lgkmcnt(0)
	s_addk_i32 s0, 0x100
	s_cmpk_lg_i32 s0, 0x400
	s_waitcnt lgkmcnt(3)
	v_mfma_f32_32x32x16_bf16 v[2:17], v[22:25], v[66:69], v[2:17]
	s_waitcnt lgkmcnt(2)
	v_mfma_f32_32x32x16_bf16 v[2:17], v[26:29], v[70:73], v[2:17]
	s_waitcnt lgkmcnt(1)
	v_mfma_f32_32x32x16_bf16 v[2:17], v[30:33], v[74:77], v[2:17]
	s_nop 11
	v_max_f32_e32 v2, 0, v2
	v_max_f32_e32 v3, 0, v3
	s_waitcnt lgkmcnt(0)
	v_fmac_f32_e32 v34, v78, v2
	v_fmac_f32_e32 v35, v78, v3
	v_max_f32_e32 v2, 0, v4
	v_max_f32_e32 v3, 0, v5
	v_fmac_f32_e32 v36, v78, v2
	v_fmac_f32_e32 v37, v78, v3
	v_max_f32_e32 v2, 0, v6
	v_max_f32_e32 v3, 0, v7
	v_fmac_f32_e32 v38, v78, v2
	v_fmac_f32_e32 v39, v78, v3
	v_max_f32_e32 v2, 0, v8
	v_max_f32_e32 v3, 0, v9
	v_fmac_f32_e32 v40, v78, v2
	v_fmac_f32_e32 v41, v78, v3
	v_max_f32_e32 v2, 0, v10
	v_max_f32_e32 v3, 0, v11
	v_fmac_f32_e32 v42, v78, v2
	v_fmac_f32_e32 v43, v78, v3
	v_max_f32_e32 v2, 0, v12
	v_max_f32_e32 v3, 0, v13
	v_fmac_f32_e32 v44, v78, v2
	v_fmac_f32_e32 v45, v78, v3
	v_max_f32_e32 v2, 0, v14
	v_max_f32_e32 v3, 0, v15
	v_fmac_f32_e32 v46, v78, v2
	v_fmac_f32_e32 v47, v78, v3
	v_max_f32_e32 v2, 0, v16
	v_max_f32_e32 v3, 0, v17
	v_fmac_f32_e32 v48, v78, v2
	v_fmac_f32_e32 v49, v78, v3
	ds_read_b128 v[2:5], v79 offset:128
	ds_read_b128 v[66:69], v79 offset:160
	ds_read_b128 v[70:73], v79 offset:192
	ds_read_b128 v[74:77], v79 offset:224
	ds_read_b32 v78, v80 offset:128
	s_waitcnt lgkmcnt(4)
	v_mfma_f32_32x32x16_bf16 v[2:17], v[18:21], v[2:5], 0
	s_waitcnt lgkmcnt(0)
	s_waitcnt lgkmcnt(3)
	v_mfma_f32_32x32x16_bf16 v[2:17], v[22:25], v[66:69], v[2:17]
	s_waitcnt lgkmcnt(2)
	v_mfma_f32_32x32x16_bf16 v[2:17], v[26:29], v[70:73], v[2:17]
	s_waitcnt lgkmcnt(1)
	v_mfma_f32_32x32x16_bf16 v[2:17], v[30:33], v[74:77], v[2:17]
	s_nop 11
	v_max_f32_e32 v2, 0, v2
	v_max_f32_e32 v3, 0, v3
	s_waitcnt lgkmcnt(0)
	v_fmac_f32_e32 v34, v78, v2
	v_fmac_f32_e32 v35, v78, v3
	v_max_f32_e32 v2, 0, v4
	v_max_f32_e32 v3, 0, v5
	v_fmac_f32_e32 v36, v78, v2
	v_fmac_f32_e32 v37, v78, v3
	v_max_f32_e32 v2, 0, v6
	v_max_f32_e32 v3, 0, v7
	v_fmac_f32_e32 v38, v78, v2
	v_fmac_f32_e32 v39, v78, v3
	v_max_f32_e32 v2, 0, v8
	v_max_f32_e32 v3, 0, v9
	v_fmac_f32_e32 v40, v78, v2
	v_fmac_f32_e32 v41, v78, v3
	v_max_f32_e32 v2, 0, v10
	v_max_f32_e32 v3, 0, v11
	v_fmac_f32_e32 v42, v78, v2
	v_fmac_f32_e32 v43, v78, v3
	v_max_f32_e32 v2, 0, v12
	v_max_f32_e32 v3, 0, v13
	v_fmac_f32_e32 v44, v78, v2
	v_fmac_f32_e32 v45, v78, v3
	v_max_f32_e32 v2, 0, v14
	v_max_f32_e32 v3, 0, v15
	v_fmac_f32_e32 v46, v78, v2
	v_fmac_f32_e32 v47, v78, v3
	v_max_f32_e32 v2, 0, v16
	v_max_f32_e32 v3, 0, v17
	v_fmac_f32_e32 v48, v78, v2
	v_fmac_f32_e32 v49, v78, v3
	s_cbranch_scc1 .LBB0_456
; DI void a1_task(unsigned char* shm, const bf16_t* prm, const bf16_t* prt, unsigned* mask, int b, int qt, const int tid) {
;     ...
;             for (int i = 0; i < 16; ++i) {
;                 const int s = s0 + 16 * (i >> 3) + 8 * h + (i & 7);
;                 const unsigned u = __float_as_uint(idx[i] + 0.0f);
;                 const unsigned k = (u & 0x80000000u) ? ~u : (u | 0x80000000u);
;                 key[jt][i] = (s <= t0 + r) ? k : 0u;
;             }
	v_pk_add_f32 v[2:3], v[48:49], 0 op_sel_hi:[1,0]
	v_lshl_or_b32 v18, s40, 5, v98
	v_and_b32_e32 v5, 0x7fffffff, v3
	v_and_b32_e32 v4, 0x7fffffff, v2
	v_xor_b32_e32 v8, -1, v3
	v_pk_add_f32 v[4:5], v[4:5], 0 neg_lo:[1,1] neg_hi:[1,1]
	v_cmp_gt_i32_e32 vcc, 0, v3
	v_or_b32_e32 v7, 22, v18
	v_xor_b32_e32 v9, -1, v2
	v_cndmask_b32_e32 v3, v5, v8, vcc
	v_cmp_gt_i32_e32 vcc, 0, v2
	v_or_b32_e32 v6, 23, v18
	v_or_b32_e32 v8, 21, v18
	v_cndmask_b32_e32 v2, v4, v9, vcc
	v_cmp_le_i32_e32 vcc, v7, v0
	v_or_b32_e32 v9, 20, v18
	s_nop 0
	v_cndmask_b32_e32 v5, 0, v2, vcc
	v_cmp_le_i32_e32 vcc, v6, v0
	s_nop 1
	v_cndmask_b32_e32 v4, 0, v3, vcc
	v_pk_add_f32 v[2:3], v[46:47], 0 op_sel_hi:[1,0]
	s_nop 0
	v_and_b32_e32 v7, 0x7fffffff, v3
	v_and_b32_e32 v6, 0x7fffffff, v2
	v_xor_b32_e32 v10, -1, v3
	v_pk_add_f32 v[6:7], v[6:7], 0 neg_lo:[1,1] neg_hi:[1,1]
	v_cmp_gt_i32_e32 vcc, 0, v3
	v_xor_b32_e32 v11, -1, v2
	s_nop 0
	v_cndmask_b32_e32 v3, v7, v10, vcc
	v_cmp_gt_i32_e32 vcc, 0, v2
	v_or_b32_e32 v10, 19, v18
	s_nop 0
	v_cndmask_b32_e32 v2, v6, v11, vcc
	v_cmp_le_i32_e32 vcc, v9, v0
	v_or_b32_e32 v11, 18, v18
	s_nop 0
	v_cndmask_b32_e32 v7, 0, v2, vcc
	v_cmp_le_i32_e32 vcc, v8, v0
	s_nop 1
	v_cndmask_b32_e32 v6, 0, v3, vcc
	v_pk_add_f32 v[2:3], v[44:45], 0 op_sel_hi:[1,0]
	s_nop 0
	v_and_b32_e32 v9, 0x7fffffff, v3
	v_and_b32_e32 v8, 0x7fffffff, v2
	v_xor_b32_e32 v12, -1, v3
	v_pk_add_f32 v[8:9], v[8:9], 0 neg_lo:[1,1] neg_hi:[1,1]
	v_cmp_gt_i32_e32 vcc, 0, v3
	v_xor_b32_e32 v13, -1, v2
	s_nop 0
	v_cndmask_b32_e32 v3, v9, v12, vcc
	v_cmp_gt_i32_e32 vcc, 0, v2
	v_or_b32_e32 v12, 17, v18
	s_nop 0
	v_cndmask_b32_e32 v2, v8, v13, vcc
	v_cmp_le_i32_e32 vcc, v11, v0
	v_or_b32_e32 v13, 16, v18
	s_nop 0
	v_cndmask_b32_e32 v9, 0, v2, vcc
	v_cmp_le_i32_e32 vcc, v10, v0
	s_nop 1
	v_cndmask_b32_e32 v8, 0, v3, vcc
	v_pk_add_f32 v[2:3], v[42:43], 0 op_sel_hi:[1,0]
	s_nop 0
	v_and_b32_e32 v11, 0x7fffffff, v3
	v_and_b32_e32 v10, 0x7fffffff, v2
	v_xor_b32_e32 v14, -1, v3
	v_pk_add_f32 v[10:11], v[10:11], 0 neg_lo:[1,1] neg_hi:[1,1]
	v_cmp_gt_i32_e32 vcc, 0, v3
	v_xor_b32_e32 v15, -1, v2
	s_nop 0
	v_cndmask_b32_e32 v3, v11, v14, vcc
	v_cmp_gt_i32_e32 vcc, 0, v2
	v_or_b32_e32 v14, 7, v18
	s_nop 0
	v_cndmask_b32_e32 v2, v10, v15, vcc
	v_cmp_le_i32_e32 vcc, v13, v0
	v_or_b32_e32 v15, 6, v18
	s_nop 0
	v_cndmask_b32_e32 v11, 0, v2, vcc
	v_cmp_le_i32_e32 vcc, v12, v0
	s_nop 1
	v_cndmask_b32_e32 v10, 0, v3, vcc
	v_pk_add_f32 v[2:3], v[40:41], 0 op_sel_hi:[1,0]
	s_nop 0
	v_and_b32_e32 v13, 0x7fffffff, v3
	v_and_b32_e32 v12, 0x7fffffff, v2
	v_xor_b32_e32 v16, -1, v3
	v_pk_add_f32 v[12:13], v[12:13], 0 neg_lo:[1,1] neg_hi:[1,1]
	v_cmp_gt_i32_e32 vcc, 0, v3
	v_xor_b32_e32 v17, -1, v2
	s_nop 0
	v_cndmask_b32_e32 v3, v13, v16, vcc
	v_cmp_gt_i32_e32 vcc, 0, v2
	v_or_b32_e32 v16, 5, v18
	s_nop 0
	v_cndmask_b32_e32 v2, v12, v17, vcc
	v_cmp_le_i32_e32 vcc, v15, v0
	v_or_b32_e32 v17, 4, v18
	s_nop 0
	v_cndmask_b32_e32 v13, 0, v2, vcc
	v_cmp_le_i32_e32 vcc, v14, v0
	s_nop 1
	v_cndmask_b32_e32 v12, 0, v3, vcc
	v_pk_add_f32 v[2:3], v[38:39], 0 op_sel_hi:[1,0]
	s_nop 0
	v_and_b32_e32 v15, 0x7fffffff, v3
	v_and_b32_e32 v14, 0x7fffffff, v2
	v_xor_b32_e32 v19, -1, v3
	v_pk_add_f32 v[14:15], v[14:15], 0 neg_lo:[1,1] neg_hi:[1,1]
	v_cmp_gt_i32_e32 vcc, 0, v3
	v_xor_b32_e32 v20, -1, v2
	s_nop 0
	v_cndmask_b32_e32 v3, v15, v19, vcc
	v_cmp_gt_i32_e32 vcc, 0, v2
	v_or_b32_e32 v19, 3, v18
	s_nop 0
	v_cndmask_b32_e32 v2, v14, v20, vcc
	v_cmp_le_i32_e32 vcc, v17, v0
	v_or_b32_e32 v20, 2, v18
	s_nop 0
	v_cndmask_b32_e32 v15, 0, v2, vcc
	v_cmp_le_i32_e32 vcc, v16, v0
	s_nop 1
	v_cndmask_b32_e32 v14, 0, v3, vcc
	v_pk_add_f32 v[2:3], v[36:37], 0 op_sel_hi:[1,0]
	s_nop 0
	v_and_b32_e32 v17, 0x7fffffff, v3
	v_and_b32_e32 v16, 0x7fffffff, v2
	v_xor_b32_e32 v21, -1, v3
	v_pk_add_f32 v[16:17], v[16:17], 0 neg_lo:[1,1] neg_hi:[1,1]
	v_cmp_gt_i32_e32 vcc, 0, v3
	v_xor_b32_e32 v22, -1, v2
	s_nop 0
	v_cndmask_b32_e32 v3, v17, v21, vcc
	v_cmp_gt_i32_e32 vcc, 0, v2
	s_nop 1
	v_cndmask_b32_e32 v2, v16, v22, vcc
	v_cmp_le_i32_e32 vcc, v20, v0
	s_nop 1
	v_cndmask_b32_e32 v17, 0, v2, vcc
	v_cmp_le_i32_e32 vcc, v19, v0
	s_nop 1
	v_cndmask_b32_e32 v16, 0, v3, vcc
	v_pk_add_f32 v[2:3], v[34:35], 0 op_sel_hi:[1,0]
	s_nop 0
	v_or_b32_e32 v19, 0x80000000, v3
	v_not_b32_e32 v20, v3
	v_cmp_gt_i32_e32 vcc, 0, v3
	s_nop 1
	v_cndmask_b32_e32 v3, v19, v20, vcc
	v_cmp_lt_i32_e32 vcc, v18, v0
	v_or_b32_e32 v19, 0x80000000, v2
	s_nop 0
	v_cndmask_b32_e32 v34, 0, v3, vcc
	v_not_b32_e32 v3, v2
	v_cmp_gt_i32_e32 vcc, 0, v2
	s_nop 1
	v_cndmask_b32_e32 v2, v19, v3, vcc
	v_cmp_le_i32_e32 vcc, v18, v0
	s_nop 1
	v_cndmask_b32_e32 v35, 0, v2, vcc
